# job_mod GEMV loop: the 8 row loads of each trip hoisted to the trip start (counted vmcnt) instead of one load in flight at a time
# speedup vs baseline: 1.0130x; 1.0048x over previous
.LBB0_94:
	s_mov_b32 s1, 0xfff40000
	v_add_co_u32_e32 v198, vcc, s1, v4
	s_nop 1
	v_addc_co_u32_e32 v199, vcc, -1, v5, vcc
	global_load_dwordx4 v[166:169], v[198:199], off nt
	s_mov_b32 s1, 0xfff70000
	v_add_co_u32_e32 v198, vcc, s1, v4
	s_nop 1
	v_addc_co_u32_e32 v199, vcc, -1, v5, vcc
	global_load_dwordx4 v[170:173], v[198:199], off nt
	s_mov_b32 s1, 0xfffa0000
	v_add_co_u32_e32 v198, vcc, s1, v4
	s_nop 1
	v_addc_co_u32_e32 v199, vcc, -1, v5, vcc
	global_load_dwordx4 v[174:177], v[198:199], off nt
	s_mov_b32 s1, 0xfffd0000
	v_add_co_u32_e32 v198, vcc, s1, v4
	s_nop 1
	v_addc_co_u32_e32 v199, vcc, -1, v5, vcc
	global_load_dwordx4 v[178:181], v[198:199], off nt
	global_load_dwordx4 v[182:185], v[4:5], off nt
	s_mov_b32 s1, 0x30000
	v_add_co_u32_e32 v198, vcc, s1, v4
	s_nop 1
	v_addc_co_u32_e32 v199, vcc, 0, v5, vcc
	global_load_dwordx4 v[186:189], v[198:199], off nt
	s_mov_b32 s1, 0x60000
	v_add_co_u32_e32 v198, vcc, s1, v4
	s_nop 1
	v_addc_co_u32_e32 v199, vcc, 0, v5, vcc
	global_load_dwordx4 v[190:193], v[198:199], off nt
	s_mov_b32 s1, 0x90000
	v_add_co_u32_e32 v198, vcc, s1, v4
	s_nop 1
	v_addc_co_u32_e32 v199, vcc, 0, v5, vcc
	global_load_dwordx4 v[194:197], v[198:199], off nt
	s_mov_b32 s1, 0xfff40000
	s_nop 0
	v_add_u32_e32 v61, s0, v60
	s_nop 0
	s_nop 0
	v_add_u32_e32 v62, 0x400, v61
	ds_read2_b32 v[74:75], v62 offset1:4
	ds_read2_b32 v[58:59], v62 offset0:8 offset1:12
	v_add_u32_e32 v63, 0x2400, v61
	v_add_u32_e32 v64, 0x4400, v61
	v_add_u32_e32 v65, 0x6400, v61
	v_add_u32_e32 v66, 0x8400, v61
	v_add_u32_e32 v67, 0xa400, v61
	v_add_u32_e32 v68, 0xc400, v61
	v_add_u32_e32 v69, 0xe400, v61
	ds_read2_b32 v[76:77], v63 offset1:4
	ds_read2_b32 v[78:79], v64 offset1:4
	ds_read2_b32 v[80:81], v65 offset1:4
	ds_read2_b32 v[82:83], v66 offset1:4
	ds_read2_b32 v[84:85], v67 offset1:4
	ds_read2_b32 v[86:87], v68 offset1:4
	ds_read2_b32 v[88:89], v69 offset1:4
	s_mov_b32 s1, 0xfff70000
	ds_read2_b32 v[128:129], v69 offset0:8 offset1:12
	ds_read2_b32 v[122:123], v68 offset0:8 offset1:12
	s_addk_i32 s0, 0x80
	s_mov_b64 s[6:7], 0x180000
	s_cmp_eq_u32 s0, 0
	s_waitcnt vmcnt(7) lgkmcnt(10)
	v_pk_fma_f32 v[54:55], v[74:75], v[166:167], v[54:55] op_sel_hi:[0,1,1]
	v_pk_fma_f32 v[56:57], v[74:75], v[168:169], v[56:57] op_sel_hi:[0,1,1]
	v_add_u32_e32 v74, 0x10400, v61
	ds_read_b32 v74, v74
	s_waitcnt lgkmcnt(9)
	v_pk_fma_f32 v[50:51], v[168:169], v[76:77], v[50:51] op_sel_hi:[1,0,1]
	s_waitcnt lgkmcnt(8)
	v_pk_fma_f32 v[46:47], v[168:169], v[78:79], v[46:47] op_sel_hi:[1,0,1]
	s_waitcnt lgkmcnt(7)
	v_pk_fma_f32 v[42:43], v[168:169], v[80:81], v[42:43] op_sel_hi:[1,0,1]
	s_waitcnt lgkmcnt(6)
	v_pk_fma_f32 v[38:39], v[168:169], v[82:83], v[38:39] op_sel_hi:[1,0,1]
	s_waitcnt lgkmcnt(5)
	v_pk_fma_f32 v[34:35], v[168:169], v[84:85], v[34:35] op_sel_hi:[1,0,1]
	s_waitcnt lgkmcnt(4)
	v_pk_fma_f32 v[30:31], v[168:169], v[86:87], v[30:31] op_sel_hi:[1,0,1]
	s_waitcnt lgkmcnt(3)
	v_pk_fma_f32 v[26:27], v[168:169], v[88:89], v[26:27] op_sel_hi:[1,0,1]
	s_waitcnt lgkmcnt(0)
	v_pk_fma_f32 v[72:73], v[168:169], v[74:75], v[22:23] op_sel_hi:[1,0,1]
	s_nop 0
	v_pk_fma_f32 v[52:53], v[166:167], v[76:77], v[52:53] op_sel_hi:[1,0,1]
	s_nop 0
	s_nop 0
	v_pk_fma_f32 v[48:49], v[166:167], v[78:79], v[48:49] op_sel_hi:[1,0,1]
	v_pk_fma_f32 v[44:45], v[166:167], v[80:81], v[44:45] op_sel_hi:[1,0,1]
	v_pk_fma_f32 v[40:41], v[166:167], v[82:83], v[40:41] op_sel_hi:[1,0,1]
	v_pk_fma_f32 v[36:37], v[166:167], v[84:85], v[36:37] op_sel_hi:[1,0,1]
	v_pk_fma_f32 v[32:33], v[166:167], v[86:87], v[32:33] op_sel_hi:[1,0,1]
	v_pk_fma_f32 v[28:29], v[166:167], v[88:89], v[28:29] op_sel_hi:[1,0,1]
	v_pk_fma_f32 v[70:71], v[166:167], v[74:75], v[24:25] op_sel_hi:[1,0,1]
	v_mov_b32_e32 v74, v75
	s_mov_b32 s1, 0xfffa0000
	s_waitcnt vmcnt(6)
	v_pk_fma_f32 v[54:55], v[74:75], v[170:171], v[54:55] op_sel_hi:[0,1,1]
	v_pk_fma_f32 v[56:57], v[74:75], v[172:173], v[56:57] op_sel_hi:[0,1,1]
	v_mov_b32_e32 v74, v77
	v_pk_fma_f32 v[52:53], v[170:171], v[74:75], v[52:53] op_sel_hi:[1,0,1]
	v_pk_fma_f32 v[50:51], v[172:173], v[74:75], v[50:51] op_sel_hi:[1,0,1]
	v_mov_b32_e32 v74, v79
	v_pk_fma_f32 v[48:49], v[170:171], v[74:75], v[48:49] op_sel_hi:[1,0,1]
	v_pk_fma_f32 v[46:47], v[172:173], v[74:75], v[46:47] op_sel_hi:[1,0,1]
	v_mov_b32_e32 v74, v81
	v_pk_fma_f32 v[44:45], v[170:171], v[74:75], v[44:45] op_sel_hi:[1,0,1]
	v_pk_fma_f32 v[42:43], v[172:173], v[74:75], v[42:43] op_sel_hi:[1,0,1]
	v_mov_b32_e32 v74, v83
	v_pk_fma_f32 v[40:41], v[170:171], v[74:75], v[40:41] op_sel_hi:[1,0,1]
	v_pk_fma_f32 v[38:39], v[172:173], v[74:75], v[38:39] op_sel_hi:[1,0,1]
	v_mov_b32_e32 v74, v85
	v_pk_fma_f32 v[36:37], v[170:171], v[74:75], v[36:37] op_sel_hi:[1,0,1]
	v_pk_fma_f32 v[34:35], v[172:173], v[74:75], v[34:35] op_sel_hi:[1,0,1]
	v_mov_b32_e32 v74, v87
	v_pk_fma_f32 v[32:33], v[170:171], v[74:75], v[32:33] op_sel_hi:[1,0,1]
	v_pk_fma_f32 v[30:31], v[172:173], v[74:75], v[30:31] op_sel_hi:[1,0,1]
	v_mov_b32_e32 v74, v89
	v_pk_fma_f32 v[28:29], v[170:171], v[74:75], v[28:29] op_sel_hi:[1,0,1]
	v_pk_fma_f32 v[26:27], v[172:173], v[74:75], v[26:27] op_sel_hi:[1,0,1]
	v_add_u32_e32 v74, 0x10410, v61
	ds_read_b32 v74, v74
	ds_read2_b32 v[78:79], v63 offset0:8 offset1:12
	ds_read2_b32 v[80:81], v64 offset0:8 offset1:12
	ds_read2_b32 v[82:83], v65 offset0:8 offset1:12
	ds_read2_b32 v[84:85], v66 offset0:8 offset1:12
	s_waitcnt lgkmcnt(4)
	v_pk_fma_f32 v[70:71], v[170:171], v[74:75], v[70:71] op_sel_hi:[1,0,1]
	s_nop 0
	v_pk_fma_f32 v[72:73], v[172:173], v[74:75], v[72:73] op_sel_hi:[1,0,1]
	s_nop 0
	s_nop 0
	ds_read2_b32 v[88:89], v67 offset0:8 offset1:12
	s_mov_b32 s1, 0xfffd0000
	s_waitcnt vmcnt(5)
	v_pk_fma_f32 v[132:133], v[176:177], v[128:129], v[26:27] op_sel_hi:[1,0,1]
	v_add_u32_e32 v26, 0x10420, v61
	ds_read_b32 v26, v26
	v_pk_fma_f32 v[74:75], v[58:59], v[174:175], v[54:55] op_sel_hi:[0,1,1]
	v_pk_fma_f32 v[76:77], v[58:59], v[176:177], v[56:57] op_sel_hi:[0,1,1]
	v_add_u32_e32 v58, 0x10430, v61
	s_waitcnt lgkmcnt(5)
	v_pk_fma_f32 v[52:53], v[174:175], v[78:79], v[52:53] op_sel_hi:[1,0,1]
	s_waitcnt lgkmcnt(4)
	v_pk_fma_f32 v[48:49], v[174:175], v[80:81], v[48:49] op_sel_hi:[1,0,1]
	s_waitcnt lgkmcnt(3)
	v_pk_fma_f32 v[44:45], v[174:175], v[82:83], v[44:45] op_sel_hi:[1,0,1]
	s_waitcnt lgkmcnt(2)
	v_pk_fma_f32 v[40:41], v[174:175], v[84:85], v[40:41] op_sel_hi:[1,0,1]
	s_waitcnt lgkmcnt(1)
	v_pk_fma_f32 v[90:91], v[174:175], v[88:89], v[36:37] op_sel_hi:[1,0,1]
	v_pk_fma_f32 v[124:125], v[174:175], v[122:123], v[32:33] op_sel_hi:[1,0,1]
	v_pk_fma_f32 v[130:131], v[174:175], v[128:129], v[28:29] op_sel_hi:[1,0,1]
	ds_read_b32 v58, v58
	s_waitcnt lgkmcnt(1)
	v_pk_fma_f32 v[70:71], v[174:175], v[26:27], v[70:71] op_sel_hi:[1,0,1]
	s_nop 0
	v_pk_fma_f32 v[42:43], v[176:177], v[82:83], v[42:43] op_sel_hi:[1,0,1]
	s_nop 0
	s_nop 0
	v_mov_b32_e32 v28, v79
	v_mov_b32_e32 v32, v81
	v_mov_b32_e32 v36, v83
	v_pk_fma_f32 v[50:51], v[176:177], v[78:79], v[50:51] op_sel_hi:[1,0,1]
	v_pk_fma_f32 v[46:47], v[176:177], v[80:81], v[46:47] op_sel_hi:[1,0,1]
	v_pk_fma_f32 v[86:87], v[176:177], v[84:85], v[38:39] op_sel_hi:[1,0,1]
	v_pk_fma_f32 v[120:121], v[176:177], v[88:89], v[34:35] op_sel_hi:[1,0,1]
	v_pk_fma_f32 v[126:127], v[176:177], v[122:123], v[30:31] op_sel_hi:[1,0,1]
	v_pk_fma_f32 v[72:73], v[176:177], v[26:27], v[72:73] op_sel_hi:[1,0,1]
	v_mov_b32_e32 v24, v59
	s_mov_b32 s1, 0x30000
	ds_read2_b32 v[78:79], v63 offset0:16 offset1:20
	ds_read2_b32 v[80:81], v64 offset0:16 offset1:20
	ds_read2_b32 v[82:83], v65 offset0:16 offset1:20
	s_waitcnt vmcnt(4)
	v_pk_fma_f32 v[26:27], v[178:179], v[28:29], v[52:53] op_sel_hi:[1,0,1]
	v_pk_fma_f32 v[30:31], v[178:179], v[32:33], v[48:49] op_sel_hi:[1,0,1]
	v_pk_fma_f32 v[34:35], v[178:179], v[36:37], v[44:45] op_sel_hi:[1,0,1]
	v_pk_fma_f32 v[36:37], v[180:181], v[36:37], v[42:43] op_sel_hi:[1,0,1]
	v_mov_b32_e32 v42, v85
	v_mov_b32_e32 v44, v89
	v_mov_b32_e32 v48, v123
	v_mov_b32_e32 v52, v129
	v_pk_fma_f32 v[22:23], v[24:25], v[178:179], v[74:75] op_sel_hi:[0,1,1]
	v_pk_fma_f32 v[24:25], v[24:25], v[180:181], v[76:77] op_sel_hi:[0,1,1]
	v_pk_fma_f32 v[28:29], v[180:181], v[28:29], v[50:51] op_sel_hi:[1,0,1]
	v_pk_fma_f32 v[32:33], v[180:181], v[32:33], v[46:47] op_sel_hi:[1,0,1]
	v_pk_fma_f32 v[38:39], v[178:179], v[42:43], v[40:41] op_sel_hi:[1,0,1]
	v_pk_fma_f32 v[40:41], v[180:181], v[42:43], v[86:87] op_sel_hi:[1,0,1]
	v_pk_fma_f32 v[42:43], v[178:179], v[44:45], v[90:91] op_sel_hi:[1,0,1]
	v_pk_fma_f32 v[44:45], v[180:181], v[44:45], v[120:121] op_sel_hi:[1,0,1]
	v_pk_fma_f32 v[46:47], v[178:179], v[48:49], v[124:125] op_sel_hi:[1,0,1]
	v_pk_fma_f32 v[48:49], v[180:181], v[48:49], v[126:127] op_sel_hi:[1,0,1]
	v_pk_fma_f32 v[50:51], v[178:179], v[52:53], v[130:131] op_sel_hi:[1,0,1]
	v_pk_fma_f32 v[52:53], v[180:181], v[52:53], v[132:133] op_sel_hi:[1,0,1]
	s_waitcnt lgkmcnt(3)
	v_pk_fma_f32 v[54:55], v[178:179], v[58:59], v[70:71] op_sel_hi:[1,0,1]
	v_pk_fma_f32 v[56:57], v[180:181], v[58:59], v[72:73] op_sel_hi:[1,0,1]
	ds_read2_b32 v[58:59], v62 offset0:16 offset1:20
	ds_read2_b32 v[84:85], v66 offset0:16 offset1:20
	ds_read2_b32 v[86:87], v67 offset0:16 offset1:20
	ds_read2_b32 v[88:89], v68 offset0:16 offset1:20
	ds_read2_b32 v[90:91], v69 offset0:16 offset1:20
	s_waitcnt vmcnt(3) lgkmcnt(4)
	v_pk_fma_f32 v[74:75], v[58:59], v[182:183], v[22:23] op_sel_hi:[0,1,1]
	v_add_u32_e32 v22, 0x10440, v61
	ds_read_b32 v22, v22
	v_pk_fma_f32 v[76:77], v[58:59], v[184:185], v[24:25] op_sel_hi:[0,1,1]
	v_pk_fma_f32 v[26:27], v[182:183], v[78:79], v[26:27] op_sel_hi:[1,0,1]
	v_pk_fma_f32 v[28:29], v[184:185], v[78:79], v[28:29] op_sel_hi:[1,0,1]
	v_pk_fma_f32 v[32:33], v[184:185], v[80:81], v[32:33] op_sel_hi:[1,0,1]
	s_waitcnt lgkmcnt(0)
	v_pk_fma_f32 v[54:55], v[182:183], v[22:23], v[54:55] op_sel_hi:[1,0,1]
	v_pk_fma_f32 v[56:57], v[184:185], v[22:23], v[56:57] op_sel_hi:[1,0,1]
	s_nop 0
	v_pk_fma_f32 v[36:37], v[184:185], v[82:83], v[36:37] op_sel_hi:[1,0,1]
	s_nop 0
	s_nop 0
	v_pk_fma_f32 v[40:41], v[184:185], v[84:85], v[40:41] op_sel_hi:[1,0,1]
	v_pk_fma_f32 v[44:45], v[184:185], v[86:87], v[44:45] op_sel_hi:[1,0,1]
	v_pk_fma_f32 v[48:49], v[184:185], v[88:89], v[48:49] op_sel_hi:[1,0,1]
	v_pk_fma_f32 v[52:53], v[184:185], v[90:91], v[52:53] op_sel_hi:[1,0,1]
	v_mov_b32_e32 v72, v79
	v_pk_fma_f32 v[30:31], v[182:183], v[80:81], v[30:31] op_sel_hi:[1,0,1]
	v_pk_fma_f32 v[34:35], v[182:183], v[82:83], v[34:35] op_sel_hi:[1,0,1]
	v_pk_fma_f32 v[38:39], v[182:183], v[84:85], v[38:39] op_sel_hi:[1,0,1]
	v_pk_fma_f32 v[42:43], v[182:183], v[86:87], v[42:43] op_sel_hi:[1,0,1]
	v_pk_fma_f32 v[46:47], v[182:183], v[88:89], v[46:47] op_sel_hi:[1,0,1]
	v_pk_fma_f32 v[50:51], v[182:183], v[90:91], v[50:51] op_sel_hi:[1,0,1]
	v_mov_b32_e32 v58, v59
	s_mov_b32 s1, 0x60000
	ds_read2_b32 v[78:79], v65 offset0:24 offset1:28
	s_waitcnt vmcnt(2)
	v_pk_fma_f32 v[26:27], v[186:187], v[72:73], v[26:27] op_sel_hi:[1,0,1]
	v_pk_fma_f32 v[28:29], v[188:189], v[72:73], v[28:29] op_sel_hi:[1,0,1]
	v_mov_b32_e32 v72, v81
	v_pk_fma_f32 v[30:31], v[186:187], v[72:73], v[30:31] op_sel_hi:[1,0,1]
	v_pk_fma_f32 v[32:33], v[188:189], v[72:73], v[32:33] op_sel_hi:[1,0,1]
	v_mov_b32_e32 v72, v83
	v_pk_fma_f32 v[34:35], v[186:187], v[72:73], v[34:35] op_sel_hi:[1,0,1]
	v_pk_fma_f32 v[36:37], v[188:189], v[72:73], v[36:37] op_sel_hi:[1,0,1]
	v_mov_b32_e32 v72, v85
	v_pk_fma_f32 v[38:39], v[186:187], v[72:73], v[38:39] op_sel_hi:[1,0,1]
	v_pk_fma_f32 v[40:41], v[188:189], v[72:73], v[40:41] op_sel_hi:[1,0,1]
	v_mov_b32_e32 v72, v87
	v_pk_fma_f32 v[42:43], v[186:187], v[72:73], v[42:43] op_sel_hi:[1,0,1]
	v_pk_fma_f32 v[44:45], v[188:189], v[72:73], v[44:45] op_sel_hi:[1,0,1]
	v_mov_b32_e32 v72, v89
	v_pk_fma_f32 v[46:47], v[186:187], v[72:73], v[46:47] op_sel_hi:[1,0,1]
	v_pk_fma_f32 v[48:49], v[188:189], v[72:73], v[48:49] op_sel_hi:[1,0,1]
	v_mov_b32_e32 v72, v91
	v_pk_fma_f32 v[50:51], v[186:187], v[72:73], v[50:51] op_sel_hi:[1,0,1]
	v_pk_fma_f32 v[52:53], v[188:189], v[72:73], v[52:53] op_sel_hi:[1,0,1]
	v_add_u32_e32 v72, 0x10450, v61
	ds_read_b32 v72, v72
	v_pk_fma_f32 v[70:71], v[58:59], v[186:187], v[74:75] op_sel_hi:[0,1,1]
	v_pk_fma_f32 v[58:59], v[58:59], v[188:189], v[76:77] op_sel_hi:[0,1,1]
	ds_read2_b32 v[80:81], v66 offset0:24 offset1:28
	ds_read2_b32 v[74:75], v63 offset0:24 offset1:28
	s_waitcnt lgkmcnt(2)
	v_pk_fma_f32 v[54:55], v[186:187], v[72:73], v[54:55] op_sel_hi:[1,0,1]
	s_nop 0
	v_pk_fma_f32 v[56:57], v[188:189], v[72:73], v[56:57] op_sel_hi:[1,0,1]
	s_nop 0
	s_nop 0
	ds_read2_b32 v[72:73], v62 offset0:24 offset1:28
	ds_read2_b32 v[76:77], v64 offset0:24 offset1:28
	ds_read2_b32 v[66:67], v67 offset0:24 offset1:28
	ds_read2_b32 v[88:89], v68 offset0:24 offset1:28
	ds_read2_b32 v[68:69], v69 offset0:24 offset1:28
	s_mov_b32 s1, 0x90000
	s_waitcnt vmcnt(1) lgkmcnt(6)
	v_pk_fma_f32 v[82:83], v[192:193], v[80:81], v[40:41] op_sel_hi:[1,0,1]
	v_add_u32_e32 v40, 0x10460, v61
	ds_read_b32 v40, v40
	s_waitcnt lgkmcnt(5)
	v_pk_fma_f32 v[58:59], v[72:73], v[192:193], v[58:59] op_sel_hi:[0,1,1]
	v_pk_fma_f32 v[28:29], v[192:193], v[74:75], v[28:29] op_sel_hi:[1,0,1]
	s_waitcnt lgkmcnt(4)
	v_pk_fma_f32 v[32:33], v[192:193], v[76:77], v[32:33] op_sel_hi:[1,0,1]
	v_pk_fma_f32 v[36:37], v[192:193], v[78:79], v[36:37] op_sel_hi:[1,0,1]
	s_waitcnt lgkmcnt(3)
	v_pk_fma_f32 v[86:87], v[192:193], v[66:67], v[44:45] op_sel_hi:[1,0,1]
	s_waitcnt lgkmcnt(2)
	v_pk_fma_f32 v[120:121], v[192:193], v[88:89], v[48:49] op_sel_hi:[1,0,1]
	s_waitcnt lgkmcnt(1)
	v_pk_fma_f32 v[124:125], v[192:193], v[68:69], v[52:53] op_sel_hi:[1,0,1]
	s_waitcnt lgkmcnt(0)
	v_pk_fma_f32 v[126:127], v[192:193], v[40:41], v[56:57] op_sel_hi:[1,0,1]
	s_nop 0
	v_pk_fma_f32 v[70:71], v[72:73], v[190:191], v[70:71] op_sel_hi:[0,1,1]
	s_nop 0
	s_nop 0
	v_mov_b32_e32 v24, v73
	v_pk_fma_f32 v[26:27], v[190:191], v[74:75], v[26:27] op_sel_hi:[1,0,1]
	v_pk_fma_f32 v[30:31], v[190:191], v[76:77], v[30:31] op_sel_hi:[1,0,1]
	v_pk_fma_f32 v[34:35], v[190:191], v[78:79], v[34:35] op_sel_hi:[1,0,1]
	v_pk_fma_f32 v[38:39], v[190:191], v[80:81], v[38:39] op_sel_hi:[1,0,1]
	v_pk_fma_f32 v[84:85], v[190:191], v[66:67], v[42:43] op_sel_hi:[1,0,1]
	v_pk_fma_f32 v[90:91], v[190:191], v[88:89], v[46:47] op_sel_hi:[1,0,1]
	v_pk_fma_f32 v[122:123], v[190:191], v[68:69], v[50:51] op_sel_hi:[1,0,1]
	v_pk_fma_f32 v[22:23], v[190:191], v[40:41], v[54:55] op_sel_hi:[1,0,1]
	v_lshl_add_u64 v[4:5], v[4:5], 0, s[6:7]
	s_waitcnt vmcnt(0)
	v_pk_fma_f32 v[54:55], v[24:25], v[194:195], v[70:71] op_sel_hi:[0,1,1]
	v_pk_fma_f32 v[56:57], v[24:25], v[196:197], v[58:59] op_sel_hi:[0,1,1]
	v_mov_b32_e32 v24, v75
	v_pk_fma_f32 v[52:53], v[194:195], v[24:25], v[26:27] op_sel_hi:[1,0,1]
	v_pk_fma_f32 v[50:51], v[196:197], v[24:25], v[28:29] op_sel_hi:[1,0,1]
	v_mov_b32_e32 v24, v77
	v_pk_fma_f32 v[48:49], v[194:195], v[24:25], v[30:31] op_sel_hi:[1,0,1]
	v_pk_fma_f32 v[46:47], v[196:197], v[24:25], v[32:33] op_sel_hi:[1,0,1]
	v_mov_b32_e32 v24, v79
	v_pk_fma_f32 v[44:45], v[194:195], v[24:25], v[34:35] op_sel_hi:[1,0,1]
	v_pk_fma_f32 v[42:43], v[196:197], v[24:25], v[36:37] op_sel_hi:[1,0,1]
	v_mov_b32_e32 v24, v81
	v_pk_fma_f32 v[40:41], v[194:195], v[24:25], v[38:39] op_sel_hi:[1,0,1]
	v_pk_fma_f32 v[38:39], v[196:197], v[24:25], v[82:83] op_sel_hi:[1,0,1]
	v_mov_b32_e32 v24, v67
	v_pk_fma_f32 v[36:37], v[194:195], v[24:25], v[84:85] op_sel_hi:[1,0,1]
	v_pk_fma_f32 v[34:35], v[196:197], v[24:25], v[86:87] op_sel_hi:[1,0,1]
	v_mov_b32_e32 v24, v89
	v_pk_fma_f32 v[32:33], v[194:195], v[24:25], v[90:91] op_sel_hi:[1,0,1]
	v_pk_fma_f32 v[30:31], v[196:197], v[24:25], v[120:121] op_sel_hi:[1,0,1]
	v_mov_b32_e32 v24, v69
	v_pk_fma_f32 v[28:29], v[194:195], v[24:25], v[122:123] op_sel_hi:[1,0,1]
	v_pk_fma_f32 v[26:27], v[196:197], v[24:25], v[124:125] op_sel_hi:[1,0,1]
	v_add_u32_e32 v24, 0x10470, v61
	ds_read_b32 v58, v24
	s_waitcnt lgkmcnt(0)
	v_pk_fma_f32 v[24:25], v[194:195], v[58:59], v[22:23] op_sel_hi:[1,0,1]
	v_pk_fma_f32 v[22:23], v[196:197], v[58:59], v[126:127] op_sel_hi:[1,0,1]
	s_cbranch_scc0 .LBB0_94
	v_and_b32_e32 v5, 64, v118
	v_xor_b32_e32 v4, 16, v118
	v_add_u32_e32 v58, 64, v5
	v_cmp_lt_i32_e32 vcc, v4, v58
	v_xor_b32_e32 v59, 32, v118
	s_nop 0
	v_cndmask_b32_e32 v4, v118, v4, vcc
	v_lshlrev_b32_e32 v89, 2, v4
	v_cmp_lt_i32_e32 vcc, v59, v58
	ds_bpermute_b32 v58, v89, v56
	ds_bpermute_b32 v62, v89, v50
	v_cndmask_b32_e32 v60, v118, v59, vcc
	ds_bpermute_b32 v59, v89, v57
	ds_bpermute_b32 v63, v89, v51
	ds_bpermute_b32 v66, v89, v46
	ds_bpermute_b32 v67, v89, v47
	ds_bpermute_b32 v70, v89, v42
	ds_bpermute_b32 v71, v89, v43
	ds_bpermute_b32 v74, v89, v38
	ds_bpermute_b32 v75, v89, v39
	ds_bpermute_b32 v78, v89, v34
	ds_bpermute_b32 v79, v89, v35
	ds_bpermute_b32 v82, v89, v30
	ds_bpermute_b32 v83, v89, v31
	ds_bpermute_b32 v86, v89, v26
	ds_bpermute_b32 v87, v89, v27
	ds_bpermute_b32 v4, v89, v54
	ds_bpermute_b32 v5, v89, v55
	s_waitcnt lgkmcnt(14)
	v_pk_add_f32 v[58:59], v[56:57], v[58:59]
	ds_bpermute_b32 v56, v89, v52
	ds_bpermute_b32 v57, v89, v53
	v_pk_add_f32 v[50:51], v[50:51], v[62:63]
	ds_bpermute_b32 v62, v89, v48
	ds_bpermute_b32 v63, v89, v49
	s_waitcnt lgkmcnt(14)
	v_pk_add_f32 v[46:47], v[46:47], v[66:67]
	ds_bpermute_b32 v66, v89, v44
	ds_bpermute_b32 v67, v89, v45
	v_pk_add_f32 v[42:43], v[42:43], v[70:71]
	ds_bpermute_b32 v70, v89, v40
	ds_bpermute_b32 v71, v89, v41
	s_waitcnt lgkmcnt(14)
	v_pk_add_f32 v[38:39], v[38:39], v[74:75]
	ds_bpermute_b32 v74, v89, v36
	ds_bpermute_b32 v75, v89, v37
	v_pk_add_f32 v[34:35], v[34:35], v[78:79]
	ds_bpermute_b32 v78, v89, v32
	ds_bpermute_b32 v79, v89, v33
	s_waitcnt lgkmcnt(14)
	v_pk_add_f32 v[30:31], v[30:31], v[82:83]
	ds_bpermute_b32 v82, v89, v28
	ds_bpermute_b32 v83, v89, v29
	v_pk_add_f32 v[26:27], v[26:27], v[86:87]
	ds_bpermute_b32 v86, v89, v24
	ds_bpermute_b32 v87, v89, v25
	ds_bpermute_b32 v90, v89, v22
	ds_bpermute_b32 v91, v89, v23
	v_lshlrev_b32_e32 v119, 2, v60
	s_waitcnt lgkmcnt(14)
	v_pk_add_f32 v[4:5], v[54:55], v[4:5]
	v_pk_add_f32 v[52:53], v[52:53], v[56:57]
	v_pk_add_f32 v[48:49], v[48:49], v[62:63]
	s_waitcnt lgkmcnt(12)
	v_pk_add_f32 v[44:45], v[44:45], v[66:67]
	s_waitcnt lgkmcnt(10)
	v_pk_add_f32 v[40:41], v[40:41], v[70:71]
	s_waitcnt lgkmcnt(8)
	v_pk_add_f32 v[36:37], v[36:37], v[74:75]
	s_waitcnt lgkmcnt(6)
	v_pk_add_f32 v[32:33], v[32:33], v[78:79]
	s_waitcnt lgkmcnt(4)
	v_pk_add_f32 v[28:29], v[28:29], v[82:83]
	s_waitcnt lgkmcnt(2)
	v_pk_add_f32 v[24:25], v[24:25], v[86:87]
	s_waitcnt lgkmcnt(0)
	v_pk_add_f32 v[22:23], v[22:23], v[90:91]
	ds_bpermute_b32 v54, v119, v4
	ds_bpermute_b32 v55, v119, v5
	ds_bpermute_b32 v60, v119, v58
	ds_bpermute_b32 v61, v119, v59
	ds_bpermute_b32 v56, v119, v52
	ds_bpermute_b32 v57, v119, v53
	ds_bpermute_b32 v64, v119, v50
	ds_bpermute_b32 v65, v119, v51
	ds_bpermute_b32 v62, v119, v48
	ds_bpermute_b32 v63, v119, v49
	ds_bpermute_b32 v68, v119, v46
	ds_bpermute_b32 v69, v119, v47
	ds_bpermute_b32 v66, v119, v44
	ds_bpermute_b32 v67, v119, v45
	ds_bpermute_b32 v72, v119, v42
	ds_bpermute_b32 v73, v119, v43
	ds_bpermute_b32 v70, v119, v40
	ds_bpermute_b32 v71, v119, v41
	ds_bpermute_b32 v76, v119, v38
	ds_bpermute_b32 v77, v119, v39
	ds_bpermute_b32 v74, v119, v36
	ds_bpermute_b32 v75, v119, v37
	ds_bpermute_b32 v80, v119, v34
	ds_bpermute_b32 v81, v119, v35
	ds_bpermute_b32 v78, v119, v32
	ds_bpermute_b32 v79, v119, v33
	ds_bpermute_b32 v84, v119, v30
	ds_bpermute_b32 v85, v119, v31
	ds_bpermute_b32 v82, v119, v28
	ds_bpermute_b32 v83, v119, v29
	ds_bpermute_b32 v88, v119, v26
	ds_bpermute_b32 v89, v119, v27
	ds_bpermute_b32 v86, v119, v24
	ds_bpermute_b32 v87, v119, v25
	ds_bpermute_b32 v90, v119, v22
	ds_bpermute_b32 v91, v119, v23
	v_cmp_eq_u32_e32 vcc, 0, v6
	s_and_saveexec_b64 s[0:1], vcc
	s_cbranch_execz .LBB0_97
	v_and_b32_e32 v6, 60, v11
	s_movk_i32 s6, 0x900
	v_lshlrev_b32_e32 v6, 2, v6
	v_mul_lo_u32 v3, v3, s6
	s_waitcnt lgkmcnt(14)
	v_pk_add_f32 v[60:61], v[58:59], v[60:61]
	v_pk_add_f32 v[58:59], v[4:5], v[54:55]
	v_add3_u32 v3, s15, v6, v3
	v_pk_add_f32 v[54:55], v[50:51], v[64:65]
	v_pk_add_f32 v[52:53], v[52:53], v[56:57]
	v_pk_add_f32 v[50:51], v[46:47], v[68:69]
	v_pk_add_f32 v[48:49], v[48:49], v[62:63]
	v_pk_add_f32 v[46:47], v[42:43], v[72:73]
	v_pk_add_f32 v[44:45], v[44:45], v[66:67]
	v_pk_add_f32 v[42:43], v[38:39], v[76:77]
	v_pk_add_f32 v[40:41], v[40:41], v[70:71]
	s_waitcnt lgkmcnt(12)
	v_pk_add_f32 v[38:39], v[34:35], v[80:81]
	v_pk_add_f32 v[36:37], v[36:37], v[74:75]
	s_waitcnt lgkmcnt(8)
	v_pk_add_f32 v[34:35], v[30:31], v[84:85]
	v_pk_add_f32 v[32:33], v[32:33], v[78:79]
	s_waitcnt lgkmcnt(4)
	v_pk_add_f32 v[30:31], v[26:27], v[88:89]
	v_pk_add_f32 v[28:29], v[28:29], v[82:83]
	s_waitcnt lgkmcnt(0)
	v_pk_add_f32 v[26:27], v[22:23], v[90:91]
	v_pk_add_f32 v[24:25], v[24:25], v[86:87]
	ds_write_b128 v3, v[58:61]
	ds_write_b128 v3, v[52:55] offset:256
	ds_write_b128 v3, v[48:51] offset:512
	ds_write_b128 v3, v[44:47] offset:768
	ds_write_b128 v3, v[40:43] offset:1024
	ds_write_b128 v3, v[36:39] offset:1280
	ds_write_b128 v3, v[32:35] offset:1536
	ds_write_b128 v3, v[28:31] offset:1792
	ds_write_b128 v3, v[24:27] offset:2048
